# v060 + layer-0 conversion rebalanced: the 64 workgroups without an adaLN unit additionally take the down-projection items; everyone else stops at item 7040 (gridDim.x == 256 only)
# baseline (speedup 1.0000x reference)
; #define LAS __attribute__((address_space(3)))
; __global__ void __launch_bounds__(512, 2) fwd_mega(Args a) {
;     ...
;     auto convert_items = [&](int LL, int lo, int hi, int w0, int nw_, size_t wd_off) __attribute__((always_inline)) {
;         LAS float* scr = (LAS float*)(lds + wave * 16384);
;         for (int it0 = lo + w0; it0 < hi; it0 += nw_) {
;             int it = it0;
;             if (it < 2688) { const int kb = it / 168, nb = it % 168; tr_item(INF(6) + (size_t)LL * D * INC, INC, WSP(WS_WIN), 1024, 0, 32 * nb, 64 * kb, 32 * nb, scr, lane); continue; } it -= 2688;
;             if (it < 512) { const int kb = it / 32, nb = it % 32; tr_item(INF(13) + (size_t)LL * D * D, D, WSP(WS_PAB), 1024, 0, 32 * nb, 64 * kb, 32 * nb, scr, lane); continue; } it -= 512;
;             if (it < 512) { const int kb = it / 32, nb = it % 32; tr_item(INF(12) + (size_t)LL * D * D, D, WSP(WS_PAB), 1024, 0, 1024 + 32 * nb, 64 * kb, 32 * nb, scr, lane); continue; } it -= 512;
;             if (it < 512) { const int kb = it / 32, nb = it % 32; tr_item(INF(14) + (size_t)LL * D * D, D, WSP(WS_WO2), 1024, 0, 32 * nb, 64 * kb, 32 * nb, scr, lane); continue; } it -= 512;
;             if (it < 1408) { const int kb = it / 88, nb = it % 88, n0 = 32 * nb; tr_item(INF(16) + (size_t)LL * D * FF, FF, WSP(WS_WGU), 1024, 0, (n0 >> 7) * 256 + (n0 & 127), 64 * kb, n0, scr, lane); continue; } it -= 1408;
;             if (it < 1408) { const int kb = it / 88, nb = it % 88, n0 = 32 * nb; tr_item(INF(17) + (size_t)LL * D * FF, FF, WSP(WS_WGU), 1024, 0, (n0 >> 7) * 256 + 128 + (n0 & 127), 64 * kb, n0, scr, lane); continue; } it -= 1408;
;             { const int kb = it / 32, nb = it % 32; tr_item(INF(20) + (size_t)LL * FF * D, D, WSP(wd_off), 2816, 0, 32 * nb, 64 * kb, 32 * nb, scr, lane); }
;         }
;     };
;     ...
;         if constexpr (l == 0) {
;             convert_items(0, 0, 8448, gw, NGW, WS_WD);
;             for (int it = gw; it < 160; it += NGW) sgu_wfrag_item(INF(10), (v4u*)(a.ws + WS_WF), it, lane);
.LBB0_17:
	s_or_b64 exec, exec, s[12:13]
	s_lshl_b32 s4, s2, 3
	v_writelane_b32 v246, s4, 2
	s_add_i32 s22, s24, s4
	s_lshl_b32 s4, s24, 14
	s_lshl_b32 s77, s3, 3
	s_add_i32 s4, s4, 0
	s_cmpk_lt_i32 s22, 0x2100
	v_writelane_b32 v246, s4, 3
	s_cselect_b64 s[6:7], -1, 0
	s_mov_b32 s5, 0
	v_writelane_b32 v246, s6, 4
	s_cmpk_gt_i32 s22, 0x20ff
	v_lshrrev_b32_e32 v200, 5, v114
	v_and_b32_e32 v205, 31, v0
	v_lshrrev_b32_e32 v201, 3, v114
	v_lshlrev_b32_e32 v204, 3, v0
	v_writelane_b32 v246, s7, 5
	s_cbranch_scc1 .LBB0_44
	v_readlane_b32 s6, v247, 40
	v_readlane_b32 s7, v247, 41
	s_nop 4
	s_mov_b64 s[8:9], s[26:27]
	v_mov_b32_e32 v3, 0
	v_and_b32_e32 v6, 56, v204
	v_mul_u32_u24_e32 v8, 0x84, v6
	v_lshlrev_b32_e32 v6, 1, v6
	v_mov_b32_e32 v7, v3
	s_waitcnt lgkmcnt(0)
	v_lshl_add_u64 v[26:27], s[8:9], 0, v[6:7]
	v_readlane_b32 s8, v247, 32
	v_readlane_b32 s9, v247, 33
	v_readlane_b32 s10, v247, 34
	v_readlane_b32 s11, v247, 35
	s_nop 4
	v_lshlrev_b32_e32 v2, 2, v205
	v_lshl_add_u64 v[4:5], s[6:7], 0, v[2:3]
	s_mov_b64 s[6:7], 0x2580000
	v_lshl_add_u64 v[6:7], v[26:27], 0, s[6:7]
	v_readlane_b32 s6, v247, 28
	v_readlane_b32 s7, v247, 29
	s_nop 4
	v_readlane_b32 s4, v246, 3
	v_lshlrev_b32_e32 v9, 2, v201
	s_waitcnt lgkmcnt(0)
	v_lshl_add_u64 v[12:13], s[8:9], 0, v[2:3]
	v_add3_u32 v28, s4, v8, v9
	v_lshl_add_u64 v[8:9], s[10:11], 0, v[2:3]
	s_mov_b64 s[10:11], 0x1a80000
	v_lshl_add_u64 v[10:11], v[26:27], 0, s[10:11]
	v_readlane_b32 s12, v247, 12
	v_readlane_b32 s13, v247, 13
	v_readlane_b32 s8, v247, 24
	v_readlane_b32 s9, v247, 25
	v_readlane_b32 s10, v247, 26
	v_readlane_b32 s11, v247, 27
	s_nop 4
	v_lshl_add_u64 v[14:15], s[6:7], 0, v[2:3]
	s_mov_b64 s[6:7], 0x1680000
	v_mul_u32_u24_e32 v1, 0x84, v200
	v_lshl_add_u64 v[16:17], v[26:27], 0, s[6:7]
	s_mov_b64 s[6:7], 0x1280000
	v_add3_u32 v1, s4, v2, v1
	v_lshl_add_u64 v[20:21], v[26:27], 0, s[6:7]
	s_mov_b64 s[6:7], 0x800000
	v_or_b32_e32 v29, 8, v201
	v_or_b32_e32 v30, 16, v201
	v_or_b32_e32 v31, 24, v201
	s_waitcnt lgkmcnt(0)
	v_lshl_add_u64 v[18:19], s[8:9], 0, v[2:3]
	v_lshl_add_u64 v[22:23], s[10:11], 0, v[2:3]
	v_lshl_add_u64 v[24:25], s[12:13], 0, v[2:3]
	v_lshl_add_u64 v[26:27], v[26:27], 0, s[6:7]
	s_lshl_b32 s10, s22, 5
	s_lshl_b32 s11, s77, 5
	s_lshl_b32 s12, s22, 1
	s_lshl_b32 s13, s77, 1
	s_movk_i32 s14, 0x7fff
	s_mov_b32 s15, 0xffff0000
	s_movk_i32 s16, 0x5000
	s_mov_b32 s17, 0xb000
	s_mov_b32 s18, 0x10000
	s_mov_b32 s19, 0x16000
	s_mov_b32 s20, 0x1b000
	s_mov_b32 s21, 0x21000
	s_mov_b32 s23, 0x26000
	s_mov_b32 s24, 0x2c000
	s_mov_b32 s25, 0x31000
	s_mov_b32 s28, 0x37000
	s_mov_b32 s29, 0x3c000
	s_mov_b32 s30, 0x42000
	s_mov_b32 s31, 0x47000
	s_mov_b32 s34, 0x4d000
	s_mov_b32 s35, 0x52000
	s_mov_b32 s36, 0x58000
	s_mov_b32 s37, 0x5d000
	s_mov_b32 s38, 0x63000
	s_mov_b32 s39, 0x68000
	s_mov_b32 s40, 0x6e000
	s_mov_b32 s41, 0x73000
	s_mov_b32 s42, 0x79000
	s_mov_b32 s43, 0x7e000
	s_mov_b32 s44, 0x84000
	s_mov_b32 s45, 0x89000
	s_mov_b32 s46, 0x8f000
	s_mov_b32 s47, 0x94000
	s_mov_b32 s48, 0x9a000
	s_mov_b32 s49, 0x9f000
	s_mov_b32 s50, 0xa5000
	s_mov_b32 s51, 0xaa000
	s_movk_i32 s52, 0x5400
	v_add_u32_e32 v32, 0x400, v1
	v_add_u32_e32 v33, 0x800, v1
	v_add_u32_e32 v34, 0xc00, v1
	v_add_u32_e32 v35, 0x1000, v1
	v_add_u32_e32 v36, 0x1400, v1
	v_add_u32_e32 v37, 0x1800, v1
	v_add_u32_e32 v38, 0x1c00, v1
	s_movk_i32 s98, 0x2100
	s_mov_b32 s99, 0
	s_cmpk_lg_u32 s3, 0x100
	s_cbranch_scc1 .Lc0_init
	s_movk_i32 s98, 0x1b80
	s_cmpk_lt_u32 s2, 0xc0
	s_cbranch_scc1 .Lc0_init
	s_mov_b32 s99, 1
.Lc0_init:
	s_mov_b32 s53, s22
	s_branch .LBB0_20
.LBB0_19:
	s_add_i32 s53, s53, s77
	s_add_i32 s10, s10, s11
	s_add_i32 s12, s12, s13
	s_cmp_lt_i32 s53, s98
	s_cbranch_scc1 .LBB0_20
	s_cmp_lg_u32 s99, 0
	s_cbranch_scc1 .Lc0_second
	s_lshl_b32 s77, s3, 3
	s_lshl_b32 s11, s77, 5
	s_lshl_b32 s13, s77, 1
	s_branch .LBB0_44
.Lc0_second:
	s_mov_b32 s99, 0
	s_sub_i32 s53, s22, 0x600
	s_addk_i32 s53, 0x1b80
	s_movk_i32 s77, 0x200
	s_lshl_b32 s11, s77, 5
	s_lshl_b32 s13, s77, 1
	s_lshl_b32 s10, s53, 5
	s_lshl_b32 s12, s53, 1
	s_movk_i32 s98, 0x2100
